# barrier poll loops without s_sleep (tight polling of the per-XCD go word)
# speedup vs baseline: 1.0040x; 1.0021x over previous
; __device__ __forceinline__ unsigned xb_ld(unsigned* p)              { return __hip_atomic_load(p, __ATOMIC_RELAXED, __HIP_MEMORY_SCOPE_AGENT); }
; __device__ __forceinline__ unsigned xb_add(unsigned* p, unsigned v) { return __hip_atomic_fetch_add(p, v, __ATOMIC_RELAXED, __HIP_MEMORY_SCOPE_AGENT); }
; #define XB_SPIN(cond, bar) do { unsigned _sp = 0; while (cond) { __builtin_amdgcn_s_sleep(1); \
;     if ((++_sp & 255u) == 0u) { if (xb_ld(&(bar)[XB_TMO])) break; if (_sp > XB_SPIN_CAP) { atomicAdd(&(bar)[XB_TMO], 1u); break; } } } } while (0)
; __device__ __forceinline__ void xcd_barrier(const XcdBarrier& b) {
;     ...
;             else XB_SPIN(xb_ld(&bar[XB_TOPGEN]) == tg, bar);
;             __builtin_amdgcn_fence(__ATOMIC_ACQUIRE, "agent");
;             xb_add(&bar[XB_XGEN(b.x)], 1u);
;             asm volatile("s_waitcnt vmcnt(0)" ::: "memory");
;         } else {
;             XB_SPIN(xb_ld(&bar[XB_XGEN(b.x)]) == gen, bar);
;             __builtin_amdgcn_fence(__ATOMIC_ACQUIRE, "agent");
.Lgb0_poll:
	global_load_dword v4, v1, s[6:7] offset:1024 sc1
	s_waitcnt vmcnt(0)
	v_cmp_eq_u32_e32 vcc, 8, v4
	s_cbranch_vccnz .Lgb0_done

; __device__ __forceinline__ unsigned xb_ld(unsigned* p)              { return __hip_atomic_load(p, __ATOMIC_RELAXED, __HIP_MEMORY_SCOPE_AGENT); }
; __device__ __forceinline__ unsigned xb_add(unsigned* p, unsigned v) { return __hip_atomic_fetch_add(p, v, __ATOMIC_RELAXED, __HIP_MEMORY_SCOPE_AGENT); }
; #define XB_SPIN(cond, bar) do { unsigned _sp = 0; while (cond) { __builtin_amdgcn_s_sleep(1); \
;     if ((++_sp & 255u) == 0u) { if (xb_ld(&(bar)[XB_TMO])) break; if (_sp > XB_SPIN_CAP) { atomicAdd(&(bar)[XB_TMO], 1u); break; } } } } while (0)
; __device__ __forceinline__ void xcd_barrier(const XcdBarrier& b) {
;     ...
;             else XB_SPIN(xb_ld(&bar[XB_TOPGEN]) == tg, bar);
;             __builtin_amdgcn_fence(__ATOMIC_ACQUIRE, "agent");
;             xb_add(&bar[XB_XGEN(b.x)], 1u);
;             asm volatile("s_waitcnt vmcnt(0)" ::: "memory");
;         } else {
;             XB_SPIN(xb_ld(&bar[XB_XGEN(b.x)]) == gen, bar);
;             __builtin_amdgcn_fence(__ATOMIC_ACQUIRE, "agent");
	s_add_i32 s12, s12, 1
	s_cmp_lt_u32 s12, 0x10000
	s_cbranch_scc1 .Lgb0_poll

; __device__ __forceinline__ unsigned xb_ld(unsigned* p)              { return __hip_atomic_load(p, __ATOMIC_RELAXED, __HIP_MEMORY_SCOPE_AGENT); }
; __device__ __forceinline__ unsigned xb_add(unsigned* p, unsigned v) { return __hip_atomic_fetch_add(p, v, __ATOMIC_RELAXED, __HIP_MEMORY_SCOPE_AGENT); }
; #define XB_SPIN(cond, bar) do { unsigned _sp = 0; while (cond) { __builtin_amdgcn_s_sleep(1); \
;     if ((++_sp & 255u) == 0u) { if (xb_ld(&(bar)[XB_TMO])) break; if (_sp > XB_SPIN_CAP) { atomicAdd(&(bar)[XB_TMO], 1u); break; } } } } while (0)
; __device__ __forceinline__ void xcd_barrier(const XcdBarrier& b) {
;     ...
;             else XB_SPIN(xb_ld(&bar[XB_TOPGEN]) == tg, bar);
;             __builtin_amdgcn_fence(__ATOMIC_ACQUIRE, "agent");
;             xb_add(&bar[XB_XGEN(b.x)], 1u);
;             asm volatile("s_waitcnt vmcnt(0)" ::: "memory");
;         } else {
;             XB_SPIN(xb_ld(&bar[XB_XGEN(b.x)]) == gen, bar);
;             __builtin_amdgcn_fence(__ATOMIC_ACQUIRE, "agent");
.Lgb1_poll:
	global_load_dword v4, v1, s[6:7] offset:1024 sc1
	s_waitcnt vmcnt(0)
	v_cmp_eq_u32_e32 vcc, 8, v4
	s_cbranch_vccnz .Lgb1_done

; __device__ __forceinline__ unsigned xb_ld(unsigned* p)              { return __hip_atomic_load(p, __ATOMIC_RELAXED, __HIP_MEMORY_SCOPE_AGENT); }
; __device__ __forceinline__ unsigned xb_add(unsigned* p, unsigned v) { return __hip_atomic_fetch_add(p, v, __ATOMIC_RELAXED, __HIP_MEMORY_SCOPE_AGENT); }
; #define XB_SPIN(cond, bar) do { unsigned _sp = 0; while (cond) { __builtin_amdgcn_s_sleep(1); \
;     if ((++_sp & 255u) == 0u) { if (xb_ld(&(bar)[XB_TMO])) break; if (_sp > XB_SPIN_CAP) { atomicAdd(&(bar)[XB_TMO], 1u); break; } } } } while (0)
; __device__ __forceinline__ void xcd_barrier(const XcdBarrier& b) {
;     ...
;             else XB_SPIN(xb_ld(&bar[XB_TOPGEN]) == tg, bar);
;             __builtin_amdgcn_fence(__ATOMIC_ACQUIRE, "agent");
;             xb_add(&bar[XB_XGEN(b.x)], 1u);
;             asm volatile("s_waitcnt vmcnt(0)" ::: "memory");
;         } else {
;             XB_SPIN(xb_ld(&bar[XB_XGEN(b.x)]) == gen, bar);
;             __builtin_amdgcn_fence(__ATOMIC_ACQUIRE, "agent");
	s_add_i32 s10, s10, 1
	s_cmp_lt_u32 s10, 0x10000
	s_cbranch_scc1 .Lgb1_poll

; __device__ __forceinline__ unsigned xb_ld(unsigned* p)              { return __hip_atomic_load(p, __ATOMIC_RELAXED, __HIP_MEMORY_SCOPE_AGENT); }
; __device__ __forceinline__ unsigned xb_add(unsigned* p, unsigned v) { return __hip_atomic_fetch_add(p, v, __ATOMIC_RELAXED, __HIP_MEMORY_SCOPE_AGENT); }
; #define XB_SPIN(cond, bar) do { unsigned _sp = 0; while (cond) { __builtin_amdgcn_s_sleep(1); \
;     if ((++_sp & 255u) == 0u) { if (xb_ld(&(bar)[XB_TMO])) break; if (_sp > XB_SPIN_CAP) { atomicAdd(&(bar)[XB_TMO], 1u); break; } } } } while (0)
; __device__ __forceinline__ void xcd_barrier(const XcdBarrier& b) {
;     ...
;             else XB_SPIN(xb_ld(&bar[XB_TOPGEN]) == tg, bar);
;             __builtin_amdgcn_fence(__ATOMIC_ACQUIRE, "agent");
;             xb_add(&bar[XB_XGEN(b.x)], 1u);
;             asm volatile("s_waitcnt vmcnt(0)" ::: "memory");
;         } else {
;             XB_SPIN(xb_ld(&bar[XB_XGEN(b.x)]) == gen, bar);
;             __builtin_amdgcn_fence(__ATOMIC_ACQUIRE, "agent");
.Lgb2_poll:
	global_load_dword v4, v1, s[6:7] offset:1024 sc1
	s_waitcnt vmcnt(0)
	v_cmp_eq_u32_e32 vcc, 8, v4
	s_cbranch_vccnz .Lgb2_done

; __device__ __forceinline__ unsigned xb_ld(unsigned* p)              { return __hip_atomic_load(p, __ATOMIC_RELAXED, __HIP_MEMORY_SCOPE_AGENT); }
; __device__ __forceinline__ unsigned xb_add(unsigned* p, unsigned v) { return __hip_atomic_fetch_add(p, v, __ATOMIC_RELAXED, __HIP_MEMORY_SCOPE_AGENT); }
; #define XB_SPIN(cond, bar) do { unsigned _sp = 0; while (cond) { __builtin_amdgcn_s_sleep(1); \
;     if ((++_sp & 255u) == 0u) { if (xb_ld(&(bar)[XB_TMO])) break; if (_sp > XB_SPIN_CAP) { atomicAdd(&(bar)[XB_TMO], 1u); break; } } } } while (0)
; __device__ __forceinline__ void xcd_barrier(const XcdBarrier& b) {
;     ...
;             else XB_SPIN(xb_ld(&bar[XB_TOPGEN]) == tg, bar);
;             __builtin_amdgcn_fence(__ATOMIC_ACQUIRE, "agent");
;             xb_add(&bar[XB_XGEN(b.x)], 1u);
;             asm volatile("s_waitcnt vmcnt(0)" ::: "memory");
;         } else {
;             XB_SPIN(xb_ld(&bar[XB_XGEN(b.x)]) == gen, bar);
;             __builtin_amdgcn_fence(__ATOMIC_ACQUIRE, "agent");
	s_add_i32 s11, s11, 1
	s_cmp_lt_u32 s11, 0x10000
	s_cbranch_scc1 .Lgb2_poll

; __device__ __forceinline__ unsigned xb_ld(unsigned* p)              { return __hip_atomic_load(p, __ATOMIC_RELAXED, __HIP_MEMORY_SCOPE_AGENT); }
; __device__ __forceinline__ unsigned xb_add(unsigned* p, unsigned v) { return __hip_atomic_fetch_add(p, v, __ATOMIC_RELAXED, __HIP_MEMORY_SCOPE_AGENT); }
; #define XB_SPIN(cond, bar) do { unsigned _sp = 0; while (cond) { __builtin_amdgcn_s_sleep(1); \
;     if ((++_sp & 255u) == 0u) { if (xb_ld(&(bar)[XB_TMO])) break; if (_sp > XB_SPIN_CAP) { atomicAdd(&(bar)[XB_TMO], 1u); break; } } } } while (0)
; __device__ __forceinline__ void xcd_barrier(const XcdBarrier& b) {
;     ...
;             else XB_SPIN(xb_ld(&bar[XB_TOPGEN]) == tg, bar);
;             __builtin_amdgcn_fence(__ATOMIC_ACQUIRE, "agent");
;             xb_add(&bar[XB_XGEN(b.x)], 1u);
;             asm volatile("s_waitcnt vmcnt(0)" ::: "memory");
;         } else {
;             XB_SPIN(xb_ld(&bar[XB_XGEN(b.x)]) == gen, bar);
;             __builtin_amdgcn_fence(__ATOMIC_ACQUIRE, "agent");
.Lgb3_poll:
	global_load_dword v4, v1, s[8:9] offset:1024 sc1
	s_waitcnt vmcnt(0)
	v_cmp_eq_u32_e32 vcc, 8, v4
	s_cbranch_vccnz .Lgb3_done

; __device__ __forceinline__ unsigned xb_ld(unsigned* p)              { return __hip_atomic_load(p, __ATOMIC_RELAXED, __HIP_MEMORY_SCOPE_AGENT); }
; __device__ __forceinline__ unsigned xb_add(unsigned* p, unsigned v) { return __hip_atomic_fetch_add(p, v, __ATOMIC_RELAXED, __HIP_MEMORY_SCOPE_AGENT); }
; #define XB_SPIN(cond, bar) do { unsigned _sp = 0; while (cond) { __builtin_amdgcn_s_sleep(1); \
;     if ((++_sp & 255u) == 0u) { if (xb_ld(&(bar)[XB_TMO])) break; if (_sp > XB_SPIN_CAP) { atomicAdd(&(bar)[XB_TMO], 1u); break; } } } } while (0)
; __device__ __forceinline__ void xcd_barrier(const XcdBarrier& b) {
;     ...
;             else XB_SPIN(xb_ld(&bar[XB_TOPGEN]) == tg, bar);
;             __builtin_amdgcn_fence(__ATOMIC_ACQUIRE, "agent");
;             xb_add(&bar[XB_XGEN(b.x)], 1u);
;             asm volatile("s_waitcnt vmcnt(0)" ::: "memory");
;         } else {
;             XB_SPIN(xb_ld(&bar[XB_XGEN(b.x)]) == gen, bar);
;             __builtin_amdgcn_fence(__ATOMIC_ACQUIRE, "agent");
	s_add_i32 s13, s13, 1
	s_cmp_lt_u32 s13, 0x10000
	s_cbranch_scc1 .Lgb3_poll

; __device__ __forceinline__ unsigned xb_ld(unsigned* p)              { return __hip_atomic_load(p, __ATOMIC_RELAXED, __HIP_MEMORY_SCOPE_AGENT); }
; __device__ __forceinline__ unsigned xb_add(unsigned* p, unsigned v) { return __hip_atomic_fetch_add(p, v, __ATOMIC_RELAXED, __HIP_MEMORY_SCOPE_AGENT); }
; #define XB_SPIN(cond, bar) do { unsigned _sp = 0; while (cond) { __builtin_amdgcn_s_sleep(1); \
;     if ((++_sp & 255u) == 0u) { if (xb_ld(&(bar)[XB_TMO])) break; if (_sp > XB_SPIN_CAP) { atomicAdd(&(bar)[XB_TMO], 1u); break; } } } } while (0)
; __device__ __forceinline__ void xcd_barrier(const XcdBarrier& b) {
;     ...
;             else XB_SPIN(xb_ld(&bar[XB_TOPGEN]) == tg, bar);
;             __builtin_amdgcn_fence(__ATOMIC_ACQUIRE, "agent");
;             xb_add(&bar[XB_XGEN(b.x)], 1u);
;             asm volatile("s_waitcnt vmcnt(0)" ::: "memory");
;         } else {
;             XB_SPIN(xb_ld(&bar[XB_XGEN(b.x)]) == gen, bar);
;             __builtin_amdgcn_fence(__ATOMIC_ACQUIRE, "agent");
.Lgb4_poll:
	global_load_dword v36, v1, s[8:9] offset:1024 sc1
	s_waitcnt vmcnt(0)
	v_cmp_eq_u32_e32 vcc, 8, v36
	s_cbranch_vccnz .Lgb4_done

; __device__ __forceinline__ unsigned xb_ld(unsigned* p)              { return __hip_atomic_load(p, __ATOMIC_RELAXED, __HIP_MEMORY_SCOPE_AGENT); }
; __device__ __forceinline__ unsigned xb_add(unsigned* p, unsigned v) { return __hip_atomic_fetch_add(p, v, __ATOMIC_RELAXED, __HIP_MEMORY_SCOPE_AGENT); }
; #define XB_SPIN(cond, bar) do { unsigned _sp = 0; while (cond) { __builtin_amdgcn_s_sleep(1); \
;     if ((++_sp & 255u) == 0u) { if (xb_ld(&(bar)[XB_TMO])) break; if (_sp > XB_SPIN_CAP) { atomicAdd(&(bar)[XB_TMO], 1u); break; } } } } while (0)
; __device__ __forceinline__ void xcd_barrier(const XcdBarrier& b) {
;     ...
;             else XB_SPIN(xb_ld(&bar[XB_TOPGEN]) == tg, bar);
;             __builtin_amdgcn_fence(__ATOMIC_ACQUIRE, "agent");
;             xb_add(&bar[XB_XGEN(b.x)], 1u);
;             asm volatile("s_waitcnt vmcnt(0)" ::: "memory");
;         } else {
;             XB_SPIN(xb_ld(&bar[XB_XGEN(b.x)]) == gen, bar);
;             __builtin_amdgcn_fence(__ATOMIC_ACQUIRE, "agent");
	s_add_i32 s13, s13, 1
	s_cmp_lt_u32 s13, 0x10000
	s_cbranch_scc1 .Lgb4_poll

; __device__ __forceinline__ unsigned xb_ld(unsigned* p)              { return __hip_atomic_load(p, __ATOMIC_RELAXED, __HIP_MEMORY_SCOPE_AGENT); }
; __device__ __forceinline__ unsigned xb_add(unsigned* p, unsigned v) { return __hip_atomic_fetch_add(p, v, __ATOMIC_RELAXED, __HIP_MEMORY_SCOPE_AGENT); }
; #define XB_SPIN(cond, bar) do { unsigned _sp = 0; while (cond) { __builtin_amdgcn_s_sleep(1); \
;     if ((++_sp & 255u) == 0u) { if (xb_ld(&(bar)[XB_TMO])) break; if (_sp > XB_SPIN_CAP) { atomicAdd(&(bar)[XB_TMO], 1u); break; } } } } while (0)
; __device__ __forceinline__ void xcd_barrier(const XcdBarrier& b) {
;     ...
;             else XB_SPIN(xb_ld(&bar[XB_TOPGEN]) == tg, bar);
;             __builtin_amdgcn_fence(__ATOMIC_ACQUIRE, "agent");
;             xb_add(&bar[XB_XGEN(b.x)], 1u);
;             asm volatile("s_waitcnt vmcnt(0)" ::: "memory");
;         } else {
;             XB_SPIN(xb_ld(&bar[XB_XGEN(b.x)]) == gen, bar);
;             __builtin_amdgcn_fence(__ATOMIC_ACQUIRE, "agent");
.Lgb5_poll:
	global_load_dword v4, v1, s[6:7] offset:1024 sc1
	s_waitcnt vmcnt(0)
	v_cmp_eq_u32_e32 vcc, 8, v4
	s_cbranch_vccnz .Lgb5_done

; __device__ __forceinline__ unsigned xb_ld(unsigned* p)              { return __hip_atomic_load(p, __ATOMIC_RELAXED, __HIP_MEMORY_SCOPE_AGENT); }
; __device__ __forceinline__ unsigned xb_add(unsigned* p, unsigned v) { return __hip_atomic_fetch_add(p, v, __ATOMIC_RELAXED, __HIP_MEMORY_SCOPE_AGENT); }
; #define XB_SPIN(cond, bar) do { unsigned _sp = 0; while (cond) { __builtin_amdgcn_s_sleep(1); \
;     if ((++_sp & 255u) == 0u) { if (xb_ld(&(bar)[XB_TMO])) break; if (_sp > XB_SPIN_CAP) { atomicAdd(&(bar)[XB_TMO], 1u); break; } } } } while (0)
; __device__ __forceinline__ void xcd_barrier(const XcdBarrier& b) {
;     ...
;             else XB_SPIN(xb_ld(&bar[XB_TOPGEN]) == tg, bar);
;             __builtin_amdgcn_fence(__ATOMIC_ACQUIRE, "agent");
;             xb_add(&bar[XB_XGEN(b.x)], 1u);
;             asm volatile("s_waitcnt vmcnt(0)" ::: "memory");
;         } else {
;             XB_SPIN(xb_ld(&bar[XB_XGEN(b.x)]) == gen, bar);
;             __builtin_amdgcn_fence(__ATOMIC_ACQUIRE, "agent");
	s_add_i32 s13, s13, 1
	s_cmp_lt_u32 s13, 0x10000
	s_cbranch_scc1 .Lgb5_poll

; __device__ __forceinline__ unsigned xb_ld(unsigned* p)              { return __hip_atomic_load(p, __ATOMIC_RELAXED, __HIP_MEMORY_SCOPE_AGENT); }
; __device__ __forceinline__ unsigned xb_add(unsigned* p, unsigned v) { return __hip_atomic_fetch_add(p, v, __ATOMIC_RELAXED, __HIP_MEMORY_SCOPE_AGENT); }
; #define XB_SPIN(cond, bar) do { unsigned _sp = 0; while (cond) { __builtin_amdgcn_s_sleep(1); \
;     if ((++_sp & 255u) == 0u) { if (xb_ld(&(bar)[XB_TMO])) break; if (_sp > XB_SPIN_CAP) { atomicAdd(&(bar)[XB_TMO], 1u); break; } } } } while (0)
; __device__ __forceinline__ void xcd_barrier(const XcdBarrier& b) {
;     ...
;             else XB_SPIN(xb_ld(&bar[XB_TOPGEN]) == tg, bar);
;             __builtin_amdgcn_fence(__ATOMIC_ACQUIRE, "agent");
;             xb_add(&bar[XB_XGEN(b.x)], 1u);
;             asm volatile("s_waitcnt vmcnt(0)" ::: "memory");
;         } else {
;             XB_SPIN(xb_ld(&bar[XB_XGEN(b.x)]) == gen, bar);
;             __builtin_amdgcn_fence(__ATOMIC_ACQUIRE, "agent");
.Lgb8_poll:
	global_load_dword v3, v0, s[4:5] offset:1024 sc1
	s_waitcnt vmcnt(0)
	v_cmp_eq_u32_e32 vcc, 8, v3
	s_cbranch_vccnz .Lgb8_done

; __device__ __forceinline__ unsigned xb_ld(unsigned* p)              { return __hip_atomic_load(p, __ATOMIC_RELAXED, __HIP_MEMORY_SCOPE_AGENT); }
; __device__ __forceinline__ unsigned xb_add(unsigned* p, unsigned v) { return __hip_atomic_fetch_add(p, v, __ATOMIC_RELAXED, __HIP_MEMORY_SCOPE_AGENT); }
; #define XB_SPIN(cond, bar) do { unsigned _sp = 0; while (cond) { __builtin_amdgcn_s_sleep(1); \
;     if ((++_sp & 255u) == 0u) { if (xb_ld(&(bar)[XB_TMO])) break; if (_sp > XB_SPIN_CAP) { atomicAdd(&(bar)[XB_TMO], 1u); break; } } } } while (0)
; __device__ __forceinline__ void xcd_barrier(const XcdBarrier& b) {
;     ...
;             else XB_SPIN(xb_ld(&bar[XB_TOPGEN]) == tg, bar);
;             __builtin_amdgcn_fence(__ATOMIC_ACQUIRE, "agent");
;             xb_add(&bar[XB_XGEN(b.x)], 1u);
;             asm volatile("s_waitcnt vmcnt(0)" ::: "memory");
;         } else {
;             XB_SPIN(xb_ld(&bar[XB_XGEN(b.x)]) == gen, bar);
;             __builtin_amdgcn_fence(__ATOMIC_ACQUIRE, "agent");
	s_add_i32 s9, s9, 1
	s_cmp_lt_u32 s9, 0x10000
	s_cbranch_scc1 .Lgb8_poll
